# P1 and P9 tile order: per-round rotation of the WG-to-tile map so every WG gets the same mix of heavy (gelu / KQ-norm-rope) and light epilogues
# baseline (speedup 1.0000x reference)
.LBB0_215:
	s_ashr_i32 s7, s7, 3
	s_lshr_b32 s98, s7, 5
	s_lshl_b32 s98, s98, 1
	s_add_i32 s98, s98, s7
	s_and_b32 s98, s98, 31
	s_and_b32 s7, s7, 0xffffffe0
	s_or_b32 s7, s7, s98
	s_add_i32 s7, s25, s7
	s_ashr_i32 s22, s7, 31
	s_lshr_b32 s22, s22, 29
	s_add_i32 s22, s7, s22
	s_ashr_i32 s23, s22, 3
	s_sub_i32 s24, 0x80, s23
	s_min_i32 s24, s24, 1
	s_abs_i32 s25, s24
	v_cvt_f32_u32_e32 v0, s25
	s_sub_i32 s27, 0, s25
	s_and_b32 s22, s22, -8
	s_sub_i32 s7, s7, s22
	v_rcp_iflag_f32_e32 v0, v0
	s_abs_i32 s22, s7
	s_xor_b32 s26, s7, s24
	s_ashr_i32 s26, s26, 31
	v_mul_f32_e32 v0, 0x4f7ffffe, v0
	v_cvt_u32_f32_e32 v0, v0
	s_nop 0
	v_readfirstlane_b32 s28, v0
	s_mul_i32 s27, s27, s28
	s_mul_hi_u32 s27, s28, s27
	s_add_i32 s28, s28, s27
	s_mul_hi_u32 s27, s22, s28
	s_mul_i32 s28, s27, s25
	s_sub_i32 s22, s22, s28
	s_add_i32 s29, s27, 1
	s_sub_i32 s28, s22, s25
	s_cmp_ge_u32 s22, s25
	s_cselect_b32 s27, s29, s27
	s_cselect_b32 s22, s28, s22
	s_add_i32 s28, s27, 1
	s_cmp_ge_u32 s22, s25
	s_cselect_b32 s22, s28, s27
	s_xor_b32 s22, s22, s26
	s_sub_i32 s22, s22, s26
	s_mul_i32 s24, s22, s24
	s_sub_i32 s7, s7, s24
	s_add_i32 s24, s23, s7

.LBB0_720:
	s_add_i32 s73, s73, 1
	s_mul_i32 s6, s73, s84
	s_mul_hi_u32 s7, s73, s85
	s_add_i32 s7, s7, s6
	s_mul_i32 s6, s73, s85
	s_add_u32 s42, s6, s33
	s_addc_u32 s43, s7, s86
	v_mov_b64_e32 v[0:1], 0x900
	v_cmp_lt_i64_e64 s[6:7], s[42:43], v[0:1]
	v_mov_b64_e32 v[0:1], 0x8ff
	v_cmp_gt_i64_e32 vcc, s[42:43], v[0:1]
	s_cbranch_vccnz .LBB0_722
	s_ashr_i32 s9, s42, 31
	s_lshr_b32 s9, s9, 29
	s_add_i32 s9, s42, s9
	s_ashr_i32 s38, s9, 3
	s_lshr_b32 s98, s38, 5
	s_add_i32 s98, s98, s38
	s_and_b32 s98, s98, 31
	s_and_b32 s38, s38, 0xffffffe0
	s_or_b32 s38, s38, s98
	s_and_b32 s9, s9, -8
	s_sub_i32 s9, s42, s9
	s_cmp_lt_i32 s9, 0
	s_cselect_b32 s39, s87, 0x120
	s_mul_i32 s9, s9, s39
	s_add_i32 s9, s9, s38
	s_mul_hi_i32 s38, s9, 0x38e38e39
	s_lshr_b32 s39, s38, 31
	s_ashr_i32 s38, s38, 2
	s_add_i32 s39, s38, s39
	s_sub_i32 s38, 0x80, s39
	s_min_i32 s40, s38, 1
	s_abs_i32 s38, s40
	v_cvt_f32_u32_e32 v0, s38
	s_sub_i32 s43, 0, s38
	s_mul_i32 s41, s39, 18
	s_sub_i32 s9, s9, s41
	v_rcp_iflag_f32_e32 v0, v0
	s_abs_i32 s42, s9
	s_xor_b32 s41, s9, s40
	s_ashr_i32 s41, s41, 31
	v_mul_f32_e32 v0, 0x4f7ffffe, v0
	v_cvt_u32_f32_e32 v0, v0
	s_nop 0
	v_readfirstlane_b32 s46, v0
	s_mul_i32 s43, s43, s46
	s_mul_hi_u32 s43, s46, s43
	s_add_i32 s46, s46, s43
	s_mul_hi_u32 s43, s42, s46
	s_mul_i32 s46, s43, s38
	s_sub_i32 s42, s42, s46
	s_add_i32 s47, s43, 1
	s_sub_i32 s46, s42, s38
	s_cmp_ge_u32 s42, s38
	s_cselect_b32 s43, s47, s43
	s_cselect_b32 s42, s46, s42
	s_add_i32 s46, s43, 1
	s_cmp_ge_u32 s42, s38
	s_cselect_b32 s38, s46, s43
	s_xor_b32 s38, s38, s41
	s_sub_i32 s38, s38, s41
	s_mul_i32 s40, s38, s40
	s_sub_i32 s9, s9, s40
	s_add_i32 s40, s39, s9
